# v16: v15 + static s_setprio 1 for waves 4-7 from the mixer phase on
# speedup vs baseline: 1.0247x; 1.0071x over previous
.LBB0_998:
	s_or_b64 exec, exec, s[2:3]
	s_waitcnt lgkmcnt(0)
	v_mov_b32_e32 v0, v246
	v_readlane_b32 s7, v255, 18
	s_barrier
	s_getreg_b32 s39, hwreg(HW_REG_XCC_ID, 0, 4)
	v_readfirstlane_b32 s98, v246
	s_cmp_lt_u32 s98, 256
	s_cbranch_scc1 .Lmx_prio_skip
	s_setprio 1
.Lmx_prio_skip:
	s_add_u32 s2, s50, s7
	v_and_b32_e32 v2, 63, v0
	v_readlane_b32 s6, v255, 17
	s_addc_u32 s3, s51, s6
	v_lshlrev_b32_e32 v0, 2, v2
	v_mov_b32_e32 v1, v113
	v_lshl_add_u64 v[4:5], s[2:3], 0, v[0:1]
	s_add_u32 s2, s48, s7
	s_addc_u32 s3, s49, s6
	v_lshl_add_u64 v[6:7], s[2:3], 0, v[0:1]
	v_or_b32_e32 v3, 0xffffffc0, v2
	v_mov_b32_e32 v8, 0
	s_mov_b64 s[2:3], 0
	v_mov_b32_e32 v1, 0
	s_mov_b64 s[6:7], 0x100
	global_load_dword v9, v[6:7], off
	global_load_dword v10, v[4:5], off
	v_mov_b32_e32 v11, 0
	v_mov_b32_e32 v12, 0
	v_cmp_gt_u32_e32 vcc, 32, v2
	s_and_saveexec_b64 s[2:3], vcc
	global_load_dword v11, v[6:7], off offset:256
	global_load_dword v12, v[4:5], off offset:256
	s_or_b64 exec, exec, s[2:3]
	s_waitcnt vmcnt(0)
	v_max_f32_e64 v9, |v9|, |v9|
	v_max_f32_e32 v8, v8, v9
	v_max_f32_e64 v11, |v11|, |v11|
	v_max_f32_e32 v8, v8, v11
	v_max_f32_e64 v10, |v10|, |v10|
	v_max_f32_e32 v1, v1, v10
	v_max_f32_e64 v12, |v12|, |v12|
	v_max_f32_e32 v1, v1, v12
	s_or_b64 exec, exec, s[2:3]
	s_load_dwordx4 s[44:47], s[84:85], 0xa0
	s_load_dwordx2 s[10:11], s[84:85], 0xb0
	v_readlane_b32 s2, v254, 62
	v_sub_u32_e32 v3, 0xe87, v2
	v_lshrrev_b32_e32 v3, 6, v3
	v_or_b32_e32 v112, s2, v2
	v_lshlrev_b64 v[4:5], 2, v[112:113]
	s_waitcnt lgkmcnt(0)
	v_lshl_add_u64 v[6:7], s[44:45], 0, v[4:5]
	v_lshl_add_u64 v[4:5], s[46:47], 0, v[4:5]
	global_load_dword v7, v[6:7], off
	v_add_u32_e32 v10, 1, v3
	global_load_dword v6, v[4:5], off
	v_or_b32_e32 v3, 64, v2
	v_readlane_b32 s3, v254, 63
	s_mov_b32 s12, 2
	v_and_b32_e32 v9, 62, v10
	v_mov_b32_e32 v12, 0
	s_mov_b64 s[8:9], 0
	v_mov_b64_e32 v[4:5], v[2:3]
	v_mov_b32_e32 v3, 0
	v_readlane_b32 s13, v255, 10
	v_readlane_b32 s14, v255, 11
	s_nop 1
	v_add_u32_e32 v112, s13, v2
	v_lshl_add_u64 v[12:13], v[112:113], 2, s[10:11]
	s_mov_b64 s[98:99], 0x1000
	v_mov_b32_e32 v4, 0
	global_load_dword v16, v[12:13], off
	global_load_dword v17, v[12:13], off offset:256
	global_load_dword v18, v[12:13], off offset:512
	global_load_dword v19, v[12:13], off offset:768
	global_load_dword v20, v[12:13], off offset:1024
	global_load_dword v21, v[12:13], off offset:1280
	global_load_dword v22, v[12:13], off offset:1536
	global_load_dword v23, v[12:13], off offset:1792
	global_load_dword v24, v[12:13], off offset:2048
	global_load_dword v25, v[12:13], off offset:2304
	global_load_dword v26, v[12:13], off offset:2560
	global_load_dword v27, v[12:13], off offset:2816
	global_load_dword v28, v[12:13], off offset:3072
	global_load_dword v29, v[12:13], off offset:3328
	global_load_dword v30, v[12:13], off offset:3584
	global_load_dword v31, v[12:13], off offset:3840
	v_lshl_add_u64 v[12:13], v[12:13], 0, s[98:99]
	s_waitcnt vmcnt(0)
	v_max_f32_e64 v16, |v16|, |v16|
	v_max_f32_e32 v4, v4, v16
	v_max_f32_e64 v17, |v17|, |v17|
	v_max_f32_e32 v4, v4, v17
	v_max_f32_e64 v18, |v18|, |v18|
	v_max_f32_e32 v4, v4, v18
	v_max_f32_e64 v19, |v19|, |v19|
	v_max_f32_e32 v4, v4, v19
	v_max_f32_e64 v20, |v20|, |v20|
	v_max_f32_e32 v4, v4, v20
	v_max_f32_e64 v21, |v21|, |v21|
	v_max_f32_e32 v4, v4, v21
	v_max_f32_e64 v22, |v22|, |v22|
	v_max_f32_e32 v4, v4, v22
	v_max_f32_e64 v23, |v23|, |v23|
	v_max_f32_e32 v4, v4, v23
	v_max_f32_e64 v24, |v24|, |v24|
	v_max_f32_e32 v4, v4, v24
	v_max_f32_e64 v25, |v25|, |v25|
	v_max_f32_e32 v4, v4, v25
	v_max_f32_e64 v26, |v26|, |v26|
	v_max_f32_e32 v4, v4, v26
	v_max_f32_e64 v27, |v27|, |v27|
	v_max_f32_e32 v4, v4, v27
	v_max_f32_e64 v28, |v28|, |v28|
	v_max_f32_e32 v4, v4, v28
	v_max_f32_e64 v29, |v29|, |v29|
	v_max_f32_e32 v4, v4, v29
	v_max_f32_e64 v30, |v30|, |v30|
	v_max_f32_e32 v4, v4, v30
	v_max_f32_e64 v31, |v31|, |v31|
	v_max_f32_e32 v4, v4, v31
	global_load_dword v16, v[12:13], off
	global_load_dword v17, v[12:13], off offset:256
	global_load_dword v18, v[12:13], off offset:512
	global_load_dword v19, v[12:13], off offset:768
	global_load_dword v20, v[12:13], off offset:1024
	global_load_dword v21, v[12:13], off offset:1280
	global_load_dword v22, v[12:13], off offset:1536
	global_load_dword v23, v[12:13], off offset:1792
	global_load_dword v24, v[12:13], off offset:2048
	global_load_dword v25, v[12:13], off offset:2304
	global_load_dword v26, v[12:13], off offset:2560
	global_load_dword v27, v[12:13], off offset:2816
	global_load_dword v28, v[12:13], off offset:3072
	global_load_dword v29, v[12:13], off offset:3328
	global_load_dword v30, v[12:13], off offset:3584
	global_load_dword v31, v[12:13], off offset:3840
	v_lshl_add_u64 v[12:13], v[12:13], 0, s[98:99]
	s_waitcnt vmcnt(0)
	v_max_f32_e64 v16, |v16|, |v16|
	v_max_f32_e32 v4, v4, v16
	v_max_f32_e64 v17, |v17|, |v17|
	v_max_f32_e32 v4, v4, v17
	v_max_f32_e64 v18, |v18|, |v18|
	v_max_f32_e32 v4, v4, v18
	v_max_f32_e64 v19, |v19|, |v19|
	v_max_f32_e32 v4, v4, v19
	v_max_f32_e64 v20, |v20|, |v20|
	v_max_f32_e32 v4, v4, v20
	v_max_f32_e64 v21, |v21|, |v21|
	v_max_f32_e32 v4, v4, v21
	v_max_f32_e64 v22, |v22|, |v22|
	v_max_f32_e32 v4, v4, v22
	v_max_f32_e64 v23, |v23|, |v23|
	v_max_f32_e32 v4, v4, v23
	v_max_f32_e64 v24, |v24|, |v24|
	v_max_f32_e32 v4, v4, v24
	v_max_f32_e64 v25, |v25|, |v25|
	v_max_f32_e32 v4, v4, v25
	v_max_f32_e64 v26, |v26|, |v26|
	v_max_f32_e32 v4, v4, v26
	v_max_f32_e64 v27, |v27|, |v27|
	v_max_f32_e32 v4, v4, v27
	v_max_f32_e64 v28, |v28|, |v28|
	v_max_f32_e32 v4, v4, v28
	v_max_f32_e64 v29, |v29|, |v29|
	v_max_f32_e32 v4, v4, v29
	v_max_f32_e64 v30, |v30|, |v30|
	v_max_f32_e32 v4, v4, v30
	v_max_f32_e64 v31, |v31|, |v31|
	v_max_f32_e32 v4, v4, v31
	global_load_dword v16, v[12:13], off
	global_load_dword v17, v[12:13], off offset:256
	global_load_dword v18, v[12:13], off offset:512
	global_load_dword v19, v[12:13], off offset:768
	global_load_dword v20, v[12:13], off offset:1024
	global_load_dword v21, v[12:13], off offset:1280
	global_load_dword v22, v[12:13], off offset:1536
	global_load_dword v23, v[12:13], off offset:1792
	global_load_dword v24, v[12:13], off offset:2048
	global_load_dword v25, v[12:13], off offset:2304
	global_load_dword v26, v[12:13], off offset:2560
	global_load_dword v27, v[12:13], off offset:2816
	global_load_dword v28, v[12:13], off offset:3072
	global_load_dword v29, v[12:13], off offset:3328
	global_load_dword v30, v[12:13], off offset:3584
	global_load_dword v31, v[12:13], off offset:3840
	v_lshl_add_u64 v[12:13], v[12:13], 0, s[98:99]
	s_waitcnt vmcnt(0)
	v_max_f32_e64 v16, |v16|, |v16|
	v_max_f32_e32 v4, v4, v16
	v_max_f32_e64 v17, |v17|, |v17|
	v_max_f32_e32 v4, v4, v17
	v_max_f32_e64 v18, |v18|, |v18|
	v_max_f32_e32 v4, v4, v18
	v_max_f32_e64 v19, |v19|, |v19|
	v_max_f32_e32 v4, v4, v19
	v_max_f32_e64 v20, |v20|, |v20|
	v_max_f32_e32 v4, v4, v20
	v_max_f32_e64 v21, |v21|, |v21|
	v_max_f32_e32 v4, v4, v21
	v_max_f32_e64 v22, |v22|, |v22|
	v_max_f32_e32 v4, v4, v22
	v_max_f32_e64 v23, |v23|, |v23|
	v_max_f32_e32 v4, v4, v23
	v_max_f32_e64 v24, |v24|, |v24|
	v_max_f32_e32 v4, v4, v24
	v_max_f32_e64 v25, |v25|, |v25|
	v_max_f32_e32 v4, v4, v25
	v_max_f32_e64 v26, |v26|, |v26|
	v_max_f32_e32 v4, v4, v26
	v_max_f32_e64 v27, |v27|, |v27|
	v_max_f32_e32 v4, v4, v27
	v_max_f32_e64 v28, |v28|, |v28|
	v_max_f32_e32 v4, v4, v28
	v_max_f32_e64 v29, |v29|, |v29|
	v_max_f32_e32 v4, v4, v29
	v_max_f32_e64 v30, |v30|, |v30|
	v_max_f32_e32 v4, v4, v30
	v_max_f32_e64 v31, |v31|, |v31|
	v_max_f32_e32 v4, v4, v31
	global_load_dword v16, v[12:13], off
	global_load_dword v17, v[12:13], off offset:256
	global_load_dword v18, v[12:13], off offset:512
	global_load_dword v19, v[12:13], off offset:768
	global_load_dword v20, v[12:13], off offset:1024
	global_load_dword v21, v[12:13], off offset:1280
	global_load_dword v22, v[12:13], off offset:1536
	global_load_dword v23, v[12:13], off offset:1792
	global_load_dword v24, v[12:13], off offset:2048
	global_load_dword v25, v[12:13], off offset:2304
	v_mov_b32_e32 v26, 0
	v_cmp_gt_u32_e32 vcc, 8, v2
	s_and_saveexec_b64 s[6:7], vcc
	global_load_dword v26, v[12:13], off offset:2560
	s_or_b64 exec, exec, s[6:7]
	s_waitcnt vmcnt(0)
	v_max_f32_e64 v16, |v16|, |v16|
	v_max_f32_e32 v4, v4, v16
	v_max_f32_e64 v17, |v17|, |v17|
	v_max_f32_e32 v4, v4, v17
	v_max_f32_e64 v18, |v18|, |v18|
	v_max_f32_e32 v4, v4, v18
	v_max_f32_e64 v19, |v19|, |v19|
	v_max_f32_e32 v4, v4, v19
	v_max_f32_e64 v20, |v20|, |v20|
	v_max_f32_e32 v4, v4, v20
	v_max_f32_e64 v21, |v21|, |v21|
	v_max_f32_e32 v4, v4, v21
	v_max_f32_e64 v22, |v22|, |v22|
	v_max_f32_e32 v4, v4, v22
	v_max_f32_e64 v23, |v23|, |v23|
	v_max_f32_e32 v4, v4, v23
	v_max_f32_e64 v24, |v24|, |v24|
	v_max_f32_e32 v4, v4, v24
	v_max_f32_e64 v25, |v25|, |v25|
	v_max_f32_e32 v4, v4, v25
	v_max_f32_e64 v26, |v26|, |v26|
	v_max_f32_e32 v4, v4, v26
